# attention epilogue: the four gate loads of each query half issued together (were one per store, each behind vmcnt(0))
# speedup vs baseline: 1.0205x; 1.0002x over previous
; DEV float bflo(unsigned w) { return __uint_as_float(w << 16); }
; DEV float bfhi(unsigned w) { return __uint_as_float(w & 0xffff0000u); }
; DEV float rcpf(float x) { return __builtin_amdgcn_rcpf(x); }
; DEV void attn_item(const Params& p, int bl, int head, int q0, int nkeys, char* smem, int tid) {
;     ...
; #pragma unroll
;   for (int qt = 0; qt < 2; ++qt) {
;     const float linv = rcpf(lacc[qt][0]);
;     const int j = q0 + wid * 32 + qt * 16 + fr;
;     const long r = (long)bl * NTOK + j;
; #pragma unroll
;     for (int dvf = 0; dvf < 4; ++dvf) {
;       const int col = head * 64 + dvf * 16 + fq * 4;
;       uint2 gz = *(const uint2*)(p.z + r * NINP + C_GMLA + col);
;       uint2 ov;
;       ov.x = pack2(o[dvf][qt][0] * linv * bflo(gz.x), o[dvf][qt][1] * linv * bfhi(gz.x));
;       ov.y = pack2(o[dvf][qt][2] * linv * bflo(gz.y), o[dvf][qt][3] * linv * bfhi(gz.y));
;       *(uint2*)(p.Y + r * 512 + col) = ov;
;     }
;   }
.LBB0_985:
	v_ashrrev_i32_e32 v45, 31, v44
	s_nop 5
	v_mov_b32_e32 v25, 0x900
	v_mad_u64_u32 v[26:27], s[8:9], s6, v25, v[44:45]
	v_mov_b64_e32 v[32:33], s[88:89]
	s_mul_i32 s12, s7, 0x900
	v_mad_u64_u32 v[34:35], s[8:9], v26, s33, v[32:33]
	v_add_u32_e32 v27, s12, v27
	v_mov_b32_e32 v42, v35
	v_mad_u64_u32 v[42:43], s[8:9], v27, s33, v[42:43]
	v_readlane_b32 s7, v255, 8
	v_mov_b32_e32 v35, v42
	v_rcp_f32_e32 v40, v40
	v_lshl_or_b32 v156, v84, 3, s7
	v_lshl_add_u64 v[34:35], v[34:35], 0, v[156:157]
	global_load_dwordx2 v[64:65], v[34:35], off offset:832
	global_load_dwordx2 v[66:67], v[34:35], off offset:864
	global_load_dwordx2 v[68:69], v[34:35], off offset:896
	global_load_dwordx2 v[70:71], v[34:35], off offset:928
	v_readlane_b32 s16, v254, 62
	v_lshlrev_b64 v[26:27], 10, v[26:27]
	v_pk_mul_f32 v[36:37], v[36:37], v[40:41] op_sel_hi:[1,0]
	v_pk_mul_f32 v[38:39], v[38:39], v[40:41] op_sel_hi:[1,0]
	v_readlane_b32 s17, v254, 63
	v_pk_mul_f32 v[28:29], v[28:29], v[40:41] op_sel_hi:[1,0]
	v_pk_mul_f32 v[30:31], v[30:31], v[40:41] op_sel_hi:[1,0]
	v_lshl_add_u64 v[26:27], s[16:17], 0, v[26:27]
	v_lshl_add_u64 v[26:27], v[26:27], 0, v[156:157]
	v_pk_mul_f32 v[20:21], v[20:21], v[40:41] op_sel_hi:[1,0]
	v_pk_mul_f32 v[22:23], v[22:23], v[40:41] op_sel_hi:[1,0]
	v_pk_mul_f32 v[16:17], v[16:17], v[40:41] op_sel_hi:[1,0]
	v_pk_mul_f32 v[18:19], v[18:19], v[40:41] op_sel_hi:[1,0]
	s_add_i32 s11, s11, s77
	s_cmp_lt_i32 s11, s10
	v_readlane_b32 s18, v255, 0
	v_readlane_b32 s19, v255, 1
	s_waitcnt vmcnt(3)
	v_lshlrev_b32_e32 v46, 16, v64
	v_and_b32_e32 v47, 0xffff0000, v64
	v_lshlrev_b32_e32 v42, 16, v65
	v_and_b32_e32 v43, 0xffff0000, v65
	v_pk_mul_f32 v[36:37], v[36:37], v[46:47]
	v_pk_mul_f32 v[38:39], v[38:39], v[42:43]
	v_cvt_pk_bf16_f32 v36, v36, v37
	v_cvt_pk_bf16_f32 v37, v38, v39
	global_store_dwordx2 v[26:27], v[36:37], off
	s_waitcnt vmcnt(3)
	v_lshlrev_b32_e32 v38, 16, v66
	v_and_b32_e32 v39, 0xffff0000, v66
	v_lshlrev_b32_e32 v36, 16, v67
	v_and_b32_e32 v37, 0xffff0000, v67
	v_pk_mul_f32 v[28:29], v[28:29], v[38:39]
	v_pk_mul_f32 v[30:31], v[30:31], v[36:37]
	v_cvt_pk_bf16_f32 v28, v28, v29
	v_cvt_pk_bf16_f32 v29, v30, v31
	global_store_dwordx2 v[26:27], v[28:29], off offset:32
	s_waitcnt vmcnt(3)
	v_lshlrev_b32_e32 v30, 16, v68
	v_and_b32_e32 v31, 0xffff0000, v68
	v_lshlrev_b32_e32 v28, 16, v69
	v_and_b32_e32 v29, 0xffff0000, v69
	v_pk_mul_f32 v[20:21], v[20:21], v[30:31]
	v_pk_mul_f32 v[22:23], v[22:23], v[28:29]
	v_cvt_pk_bf16_f32 v20, v20, v21
	v_cvt_pk_bf16_f32 v21, v22, v23
	global_store_dwordx2 v[26:27], v[20:21], off offset:64
	v_or_b32_e32 v22, 16, v44
	v_ashrrev_i32_e32 v23, 31, v22
	v_mad_u64_u32 v[22:23], s[6:7], s6, v25, v[22:23]
	v_mad_u64_u32 v[28:29], s[6:7], v22, s33, v[32:33]
	v_add_u32_e32 v23, s12, v23
	v_mov_b32_e32 v30, v29
	v_mad_u64_u32 v[30:31], s[6:7], v23, s33, v[30:31]
	v_mov_b32_e32 v29, v30
	v_lshl_add_u64 v[28:29], v[28:29], 0, v[156:157]
	s_waitcnt vmcnt(3)
	v_lshlrev_b32_e32 v30, 16, v70
	v_and_b32_e32 v31, 0xffff0000, v70
	v_lshlrev_b32_e32 v20, 16, v71
	v_and_b32_e32 v21, 0xffff0000, v71
	v_pk_mul_f32 v[16:17], v[16:17], v[30:31]
	v_pk_mul_f32 v[18:19], v[18:19], v[20:21]
	v_cvt_pk_bf16_f32 v16, v16, v17
	v_cvt_pk_bf16_f32 v17, v18, v19
	global_store_dwordx2 v[26:27], v[16:17], off offset:96
	global_load_dwordx2 v[72:73], v[28:29], off offset:832
	global_load_dwordx2 v[74:75], v[28:29], off offset:864
	global_load_dwordx2 v[76:77], v[28:29], off offset:896
	global_load_dwordx2 v[78:79], v[28:29], off offset:928
	v_rcp_f32_e32 v18, v24
	v_lshlrev_b64 v[20:21], 10, v[22:23]
	v_lshl_add_u64 v[20:21], s[16:17], 0, v[20:21]
	v_lshl_add_u64 v[20:21], v[20:21], 0, v[156:157]
	v_pk_mul_f32 v[12:13], v[12:13], v[18:19] op_sel_hi:[1,0]
	v_pk_mul_f32 v[14:15], v[14:15], v[18:19] op_sel_hi:[1,0]
	v_pk_mul_f32 v[8:9], v[8:9], v[18:19] op_sel_hi:[1,0]
	v_pk_mul_f32 v[10:11], v[10:11], v[18:19] op_sel_hi:[1,0]
	v_pk_mul_f32 v[4:5], v[4:5], v[18:19] op_sel_hi:[1,0]
	v_pk_mul_f32 v[6:7], v[6:7], v[18:19] op_sel_hi:[1,0]
	v_pk_mul_f32 v[0:1], v[0:1], v[18:19] op_sel_hi:[1,0]
	v_pk_mul_f32 v[2:3], v[2:3], v[18:19] op_sel_hi:[1,0]
	s_waitcnt vmcnt(3)
	v_lshlrev_b32_e32 v22, 16, v72
	v_and_b32_e32 v23, 0xffff0000, v72
	v_lshlrev_b32_e32 v16, 16, v73
	v_and_b32_e32 v17, 0xffff0000, v73
	v_pk_mul_f32 v[12:13], v[12:13], v[22:23]
	v_pk_mul_f32 v[14:15], v[14:15], v[16:17]
	v_cvt_pk_bf16_f32 v12, v12, v13
	v_cvt_pk_bf16_f32 v13, v14, v15
	global_store_dwordx2 v[20:21], v[12:13], off
	s_waitcnt vmcnt(3)
	v_lshlrev_b32_e32 v14, 16, v74
	v_and_b32_e32 v15, 0xffff0000, v74
	v_lshlrev_b32_e32 v12, 16, v75
	v_and_b32_e32 v13, 0xffff0000, v75
	v_pk_mul_f32 v[8:9], v[8:9], v[14:15]
	v_pk_mul_f32 v[10:11], v[10:11], v[12:13]
	v_cvt_pk_bf16_f32 v8, v8, v9
	v_cvt_pk_bf16_f32 v9, v10, v11
	global_store_dwordx2 v[20:21], v[8:9], off offset:32
	s_waitcnt vmcnt(3)
	v_lshlrev_b32_e32 v10, 16, v76
	v_and_b32_e32 v11, 0xffff0000, v76
	v_lshlrev_b32_e32 v8, 16, v77
	v_and_b32_e32 v9, 0xffff0000, v77
	v_pk_mul_f32 v[4:5], v[4:5], v[10:11]
	v_pk_mul_f32 v[6:7], v[6:7], v[8:9]
	v_cvt_pk_bf16_f32 v4, v4, v5
	v_cvt_pk_bf16_f32 v5, v6, v7
	global_store_dwordx2 v[20:21], v[4:5], off offset:64
	s_waitcnt vmcnt(3)
	v_lshlrev_b32_e32 v6, 16, v78
	v_and_b32_e32 v7, 0xffff0000, v78
	v_lshlrev_b32_e32 v4, 16, v79
	v_and_b32_e32 v5, 0xffff0000, v79
	v_pk_mul_f32 v[0:1], v[0:1], v[6:7]
	v_pk_mul_f32 v[2:3], v[2:3], v[4:5]
	v_cvt_pk_bf16_f32 v0, v0, v1
	v_cvt_pk_bf16_f32 v1, v2, v3
	global_store_dwordx2 v[20:21], v[0:1], off offset:96
	s_cbranch_scc0 .LBB0_977
